# gelu argument simplification also in the S5 readout epilogue (on top of FFN-up gelu, MLA skew, in_cd load hoist)
# speedup vs baseline: 1.0132x; 1.0046x over previous
; #define PG8_STAGE(bufoff, gbase, voff) do { _Pragma("unroll") for (int _i = 0; _i < 2; ++_i) \
;         __builtin_amdgcn_global_load_lds((const unsigned*)((const char*)(gbase) + (voff)[_i]), (LAS unsigned*)(lds + (bufoff) + ldsw + _i * 8192), 16, 0, 0); } while (0)
; #define PG8_LDA(dst, b, h) do { _Pragma("unroll") for (int m = 0; m < 4; ++m) _Pragma("unroll") for (int k = 0; k < 2; ++k) dst[m][k] = *(const LAS bf16x8*)(lds + PG8_SA(b, h) + aoff + m * 2048 + k * 1024); } while (0)
; #define PG8_LDB(dst, b, h) do { _Pragma("unroll") for (int n = 0; n < 2; ++n) _Pragma("unroll") for (int k = 0; k < 2; ++k) dst[n][k] = *(const LAS bf16x8*)(lds + PG8_SB(b, h) + boff + n * 2048 + k * 1024); } while (0)
; #define PG8_MMA(ai, bj, At, Bt) do { __builtin_amdgcn_s_setprio(1); _Pragma("unroll") for (int m = 0; m < 4; ++m) _Pragma("unroll") for (int n = 0; n < 2; ++n) _Pragma("unroll") for (int k = 0; k < 2; ++k) \
;         acc[ai][bj][m][n] = __builtin_amdgcn_mfma_f32_16x16x32_bf16(Bt[n][k], At[m][k], acc[ai][bj][m][n], 0, 0, 0); __builtin_amdgcn_s_setprio(0); } while (0)
; #define PG8_BAR __builtin_amdgcn_s_barrier()
; template <class Epi, class Sched, bool APERM, bool ABLK = false, bool RELAX = true>
; __device__ __forceinline__ void gemm_phase(LAS unsigned char* lds, const Gemm g, const Sched& S, const Epi& E) {
;     ...
;             PG8_LDB(B0, 0, 0); PG8_LDB(B1, 0, 1); PG8_SCHED; PG8_LDA(At, 0, 0); PG8_STAGE(PG8_SA(1, 1), a1 + hstepA, voffA);
;             PG8_WAIT_V8R; PG8_WAIT_L(0); PG8_BAR; PG8_MMA(0, 0, At, B0); PG8_MMA(0, 1, At, B1); PG8_BAR; PG8_SCHED;
;             PG8_LDA(At, 0, 1); PG8_STAGE(PG8_SB(0, 0), b2, voffB); PG8_STAGE(PG8_SB(0, 1), b2 + hstepB, voffB); PG8_STAGE(PG8_SA(0, 0), a2, voffA);
;             PG8_WAIT_V8R; PG8_FLAG(0u); PG8_WAIT_L(0); PG8_BAR; PG8_MMA(1, 0, At, B0); PG8_MMA(1, 1, At, B1); PG8_BAR; PG8_SCHED;
;             PG8_LDB(B0, 1, 0); PG8_LDB(B1, 1, 1); PG8_SCHED; PG8_LDA(At, 1, 0); PG8_STAGE(PG8_SA(0, 1), a2 + hstepA, voffA);
;             PG8_WAIT_V(8); PG8_WAIT_L(0); PG8_BAR; PG8_MMA(0, 0, At, B0); PG8_MMA(0, 1, At, B1); PG8_BAR; PG8_SCHED;
;             PG8_LDA(At, 1, 1); PG8_STAGE(PG8_SB(1, 0), b3, voffB); PG8_STAGE(PG8_SB(1, 1), b3 + hstepB, voffB); PG8_STAGE(PG8_SA(1, 0), a3, voffA);
;             PG8_WAIT_V(8); PG8_WAIT_L(0); PG8_BAR; PG8_MMA(1, 0, At, B0); PG8_MMA(1, 1, At, B1); PG8_BAR; PG8_SCHED;
.Lre9:
	s_waitcnt lgkmcnt(0)
	s_barrier
	s_setprio 1
	s_waitcnt lgkmcnt(0)
	v_mfma_f32_16x16x32_bf16 v[94:97], v[144:147], v[182:185], v[94:97]
	v_mfma_f32_16x16x32_bf16 v[90:93], v[158:161], v[182:185], v[90:93]
	v_mfma_f32_16x16x32_bf16 v[86:89], v[144:147], v[190:193], v[86:89]
	v_mfma_f32_16x16x32_bf16 v[82:85], v[158:161], v[190:193], v[82:85]
	v_mfma_f32_16x16x32_bf16 v[78:81], v[144:147], v[198:201], v[78:81]
	v_mfma_f32_16x16x32_bf16 v[74:77], v[158:161], v[198:201], v[74:77]
	v_mfma_f32_16x16x32_bf16 v[70:73], v[144:147], v[206:209], v[70:73]
	v_mfma_f32_16x16x32_bf16 v[66:69], v[158:161], v[206:209], v[66:69]
	v_mfma_f32_16x16x32_bf16 v[94:97], v[154:157], v[186:189], v[94:97]
	v_mfma_f32_16x16x32_bf16 v[90:93], v[162:165], v[186:189], v[90:93]
	v_mfma_f32_16x16x32_bf16 v[86:89], v[154:157], v[194:197], v[86:89]
	v_mfma_f32_16x16x32_bf16 v[82:85], v[162:165], v[194:197], v[82:85]
	v_mfma_f32_16x16x32_bf16 v[78:81], v[154:157], v[202:205], v[78:81]
	v_mfma_f32_16x16x32_bf16 v[74:77], v[162:165], v[202:205], v[74:77]
	v_mfma_f32_16x16x32_bf16 v[70:73], v[154:157], v[210:213], v[70:73]
	v_mfma_f32_16x16x32_bf16 v[66:69], v[162:165], v[210:213], v[66:69]
	s_setprio 0
	s_setprio 1
	v_mfma_f32_16x16x32_bf16 v[30:33], v[166:169], v[182:185], v[30:33]
	v_mfma_f32_16x16x32_bf16 v[26:29], v[174:177], v[182:185], v[26:29]
	v_mfma_f32_16x16x32_bf16 v[22:25], v[166:169], v[190:193], v[22:25]
	v_mfma_f32_16x16x32_bf16 v[18:21], v[174:177], v[190:193], v[18:21]
	v_mfma_f32_16x16x32_bf16 v[14:17], v[166:169], v[198:201], v[14:17]
	v_mfma_f32_16x16x32_bf16 v[10:13], v[174:177], v[198:201], v[10:13]
	v_mfma_f32_16x16x32_bf16 v[6:9], v[166:169], v[206:209], v[6:9]
	v_mfma_f32_16x16x32_bf16 v[2:5], v[174:177], v[206:209], v[2:5]
	v_mfma_f32_16x16x32_bf16 v[30:33], v[170:173], v[186:189], v[30:33]
	v_mfma_f32_16x16x32_bf16 v[26:29], v[178:181], v[186:189], v[26:29]
	v_mfma_f32_16x16x32_bf16 v[22:25], v[170:173], v[194:197], v[22:25]
	v_mfma_f32_16x16x32_bf16 v[18:21], v[178:181], v[194:197], v[18:21]
	v_mfma_f32_16x16x32_bf16 v[14:17], v[170:173], v[202:205], v[14:17]
	v_mfma_f32_16x16x32_bf16 v[10:13], v[178:181], v[202:205], v[10:13]
	v_mfma_f32_16x16x32_bf16 v[6:9], v[170:173], v[210:213], v[6:9]
	v_mfma_f32_16x16x32_bf16 v[2:5], v[178:181], v[210:213], v[2:5]
	s_setprio 0
	s_barrier
	s_add_i32 s83, 0, 0x18000
	v_add_u32_e32 v138, s83, v149
	s_add_i32 s85, 0, 0x1c000
	ds_read_b128 v[144:147], v138
	ds_read_b128 v[154:157], v138 offset:1024
	ds_read_b128 v[158:161], v138 offset:2048
	ds_read_b128 v[162:165], v138 offset:3072
	v_add_u32_e32 v138, s85, v149
	ds_read_b128 v[166:169], v138
	ds_read_b128 v[170:173], v138 offset:1024
	ds_read_b128 v[174:177], v138 offset:2048
	ds_read_b128 v[178:181], v138 offset:3072
	s_add_u32 s64, s64, 0x20000
	s_addc_u32 s65, s65, 0
	s_mov_b32 m0, s47
	v_lshl_add_u64 v[222:223], s[64:65], 0, v[136:137]
	ds_read_b128 v[182:185], v152 offset:32768
	ds_read_b128 v[186:189], v152 offset:33792
	ds_read_b128 v[190:193], v152 offset:34816
	ds_read_b128 v[194:197], v152 offset:35840
	ds_read_b128 v[198:201], v152 offset:36864
	ds_read_b128 v[202:205], v152 offset:37888
	ds_read_b128 v[206:209], v152 offset:38912
	ds_read_b128 v[210:213], v152 offset:39936
	global_load_lds_dwordx4 v[222:223], off
	v_lshl_add_u64 v[222:223], s[64:65], 0, v[132:133]
	s_mov_b32 m0, s48
	s_nop 0
	global_load_lds_dwordx4 v[222:223], off
	s_waitcnt vmcnt(8)
	s_waitcnt lgkmcnt(0)
	s_barrier
	s_setprio 1
	s_waitcnt lgkmcnt(0)
	v_mfma_f32_16x16x32_bf16 v[126:129], v[144:147], v[182:185], v[126:129]
	v_mfma_f32_16x16x32_bf16 v[122:125], v[158:161], v[182:185], v[122:125]
	v_mfma_f32_16x16x32_bf16 v[118:121], v[144:147], v[190:193], v[118:121]
	v_mfma_f32_16x16x32_bf16 v[114:117], v[158:161], v[190:193], v[114:117]
	v_mfma_f32_16x16x32_bf16 v[110:113], v[144:147], v[198:201], v[110:113]
	v_mfma_f32_16x16x32_bf16 v[106:109], v[158:161], v[198:201], v[106:109]
	v_mfma_f32_16x16x32_bf16 v[102:105], v[144:147], v[206:209], v[102:105]
	v_mfma_f32_16x16x32_bf16 v[98:101], v[158:161], v[206:209], v[98:101]
	v_mfma_f32_16x16x32_bf16 v[126:129], v[154:157], v[186:189], v[126:129]
	v_mfma_f32_16x16x32_bf16 v[122:125], v[162:165], v[186:189], v[122:125]
	v_mfma_f32_16x16x32_bf16 v[118:121], v[154:157], v[194:197], v[118:121]
	v_mfma_f32_16x16x32_bf16 v[114:117], v[162:165], v[194:197], v[114:117]
	v_mfma_f32_16x16x32_bf16 v[110:113], v[154:157], v[202:205], v[110:113]
	v_mfma_f32_16x16x32_bf16 v[106:109], v[162:165], v[202:205], v[106:109]
	v_mfma_f32_16x16x32_bf16 v[102:105], v[154:157], v[210:213], v[102:105]
	v_mfma_f32_16x16x32_bf16 v[98:101], v[162:165], v[210:213], v[98:101]
	s_setprio 0
	s_setprio 1
	v_mfma_f32_16x16x32_bf16 v[62:65], v[166:169], v[182:185], v[62:65]
	v_mfma_f32_16x16x32_bf16 v[58:61], v[174:177], v[182:185], v[58:61]
	v_mfma_f32_16x16x32_bf16 v[54:57], v[166:169], v[190:193], v[54:57]
	v_mfma_f32_16x16x32_bf16 v[50:53], v[174:177], v[190:193], v[50:53]
	v_mfma_f32_16x16x32_bf16 v[46:49], v[166:169], v[198:201], v[46:49]
	v_mfma_f32_16x16x32_bf16 v[42:45], v[174:177], v[198:201], v[42:45]
	v_mfma_f32_16x16x32_bf16 v[38:41], v[166:169], v[206:209], v[38:41]
	v_mfma_f32_16x16x32_bf16 v[34:37], v[174:177], v[206:209], v[34:37]
	v_mfma_f32_16x16x32_bf16 v[62:65], v[170:173], v[186:189], v[62:65]
	v_mfma_f32_16x16x32_bf16 v[58:61], v[178:181], v[186:189], v[58:61]
	v_mfma_f32_16x16x32_bf16 v[54:57], v[170:173], v[194:197], v[54:57]
	v_mfma_f32_16x16x32_bf16 v[50:53], v[178:181], v[194:197], v[50:53]
	v_mfma_f32_16x16x32_bf16 v[46:49], v[170:173], v[202:205], v[46:49]
	v_mfma_f32_16x16x32_bf16 v[42:45], v[178:181], v[202:205], v[42:45]
	v_mfma_f32_16x16x32_bf16 v[38:41], v[170:173], v[210:213], v[38:41]
	v_mfma_f32_16x16x32_bf16 v[34:37], v[178:181], v[210:213], v[34:37]
	s_setprio 0
	s_barrier
; __device__ __forceinline__ void store8(bf16_t* p, const f32x4& a, const f32x4& b) { u32x4 w; w.x = pk2(a[0], a[1]); w.y = pk2(a[2], a[3]); w.z = pk2(b[0], b[1]); w.w = pk2(b[2], b[3]); *(u32x4*)p = w; }
; __device__ __forceinline__ float gelu_t(float x) { const float u = x + 0.044715f * x * x * x; return x * __builtin_amdgcn_rcpf(1.f + __builtin_amdgcn_exp2f(-2.302208198f * u)); }
; #define PG8_STAGE(bufoff, gbase, voff) do { _Pragma("unroll") for (int _i = 0; _i < 2; ++_i) \
;         __builtin_amdgcn_global_load_lds((const unsigned*)((const char*)(gbase) + (voff)[_i]), (LAS unsigned*)(lds + (bufoff) + ldsw + _i * 8192), 16, 0, 0); } while (0)
; #define PG8_LDA(dst, b, h) do { _Pragma("unroll") for (int m = 0; m < 4; ++m) _Pragma("unroll") for (int k = 0; k < 2; ++k) dst[m][k] = *(const LAS bf16x8*)(lds + PG8_SA(b, h) + aoff + m * 2048 + k * 1024); } while (0)
; #define PG8_WAIT_V(n) asm volatile("s_waitcnt vmcnt(" #n ")" ::: "memory")
; template <class Epi, class Sched, bool APERM, bool ABLK = false, bool RELAX = true>
; __device__ __forceinline__ void gemm_phase(LAS unsigned char* lds, const Gemm g, const Sched& S, const Epi& E) {
;     ...
;             PG8_LDA(At, 1, 1); PG8_STAGE(PG8_SB(1, 0), b3, voffB); PG8_STAGE(PG8_SB(1, 1), b3 + hstepB, voffB); PG8_STAGE(PG8_SA(1, 0), a3, voffA);
;             PG8_WAIT_V(8); PG8_WAIT_L(0); PG8_BAR; PG8_MMA(1, 0, At, B0); PG8_MMA(1, 1, At, B1); PG8_BAR; PG8_SCHED;
;         }
;         if (wr == 0) PG8_BAR;
;     __device__ __forceinline__ void operator()(const f32x4 (&acc)[2][2][4][2], const pg8::Unit& u, int wr, int wc, int fr, int fq, int buf) const {
;     ...
;             bf16_t* G = (bf16_t*)(ws + R_G); const int g = u.pn, j9 = u.pm - 9 * g;
; #pragma unroll
;             for (int bj = 0; bj < 2; ++bj) { const int n0 = bj * 128 + wc * 32 + 8 * fq, t = n0 >> 4, h0 = n0 & 15;
; #pragma unroll
;                 for (int ai = 0; ai < 2; ++ai)
; #pragma unroll
;                     for (int m = 0; m < 4; ++m) { const int cr = j9 * 256 + ai * 128 + m * 16 + rloc0, b = cr / 144, c = cr - b * 144;
;                         f32x4 v0 = acc[ai][bj][m][0], v1 = acc[ai][bj][m][1];
; #pragma unroll
;                         for (int q = 0; q < 4; ++q) { v0[q] = gelu_t(v0[q]); v1[q] = gelu_t(v1[q]); }
;                         store8(G + ((size_t)b * RB + 16 * c + t) * 512 + 16 * g + h0, v0, v1); } }
	s_add_i32 s64, s83, s45
	v_lshl_add_u64 v[214:215], v[214:215], 0, s[18:19]
	s_mov_b32 m0, s64
	ds_read_b128 v[182:185], v152 offset:49152
	ds_read_b128 v[186:189], v152 offset:50176
	ds_read_b128 v[190:193], v152 offset:51200
	ds_read_b128 v[194:197], v152 offset:52224
	ds_read_b128 v[198:201], v152 offset:53248
	ds_read_b128 v[202:205], v152 offset:54272
	ds_read_b128 v[206:209], v152 offset:55296
	ds_read_b128 v[210:213], v152 offset:56320
	global_load_lds_dwordx4 v[214:215], off
	s_add_i32 m0, s64, 0x2000
	s_add_u32 s62, s62, 0x20080
	v_lshl_add_u64 v[214:215], v[216:217], 0, s[18:19]
	s_addc_u32 s63, s63, 0
	s_add_i32 s64, s85, s45
	global_load_lds_dwordx4 v[214:215], off
	v_lshl_add_u64 v[214:215], s[62:63], 0, v[134:135]
	s_mov_b32 m0, s64
	s_nop 0
	global_load_lds_dwordx4 v[214:215], off
	v_lshl_add_u64 v[214:215], s[62:63], 0, v[130:131]
	s_add_i32 m0, s64, 0x2000
	s_nop 0
	global_load_lds_dwordx4 v[214:215], off
	v_lshl_add_u64 v[214:215], v[218:219], 0, s[18:19]
	s_mov_b32 m0, s67
	s_nop 0
	global_load_lds_dwordx4 v[214:215], off
	v_lshl_add_u64 v[214:215], v[220:221], 0, s[18:19]
	s_mov_b32 m0, s68
	s_nop 0
	global_load_lds_dwordx4 v[214:215], off
	s_waitcnt vmcnt(8)
	s_waitcnt lgkmcnt(0)
	s_barrier
	s_setprio 1
	s_waitcnt lgkmcnt(0)
	v_mfma_f32_16x16x32_bf16 v[94:97], v[144:147], v[182:185], v[94:97]
	v_mfma_f32_16x16x32_bf16 v[90:93], v[158:161], v[182:185], v[90:93]
	v_mfma_f32_16x16x32_bf16 v[86:89], v[144:147], v[190:193], v[86:89]
	v_mfma_f32_16x16x32_bf16 v[82:85], v[158:161], v[190:193], v[82:85]
	v_mfma_f32_16x16x32_bf16 v[78:81], v[144:147], v[198:201], v[78:81]
	v_mfma_f32_16x16x32_bf16 v[74:77], v[158:161], v[198:201], v[74:77]
	v_mfma_f32_16x16x32_bf16 v[70:73], v[144:147], v[206:209], v[70:73]
	v_mfma_f32_16x16x32_bf16 v[66:69], v[158:161], v[206:209], v[66:69]
	v_mfma_f32_16x16x32_bf16 v[94:97], v[154:157], v[186:189], v[94:97]
	v_mfma_f32_16x16x32_bf16 v[90:93], v[162:165], v[186:189], v[90:93]
	v_mfma_f32_16x16x32_bf16 v[86:89], v[154:157], v[194:197], v[86:89]
	v_mfma_f32_16x16x32_bf16 v[82:85], v[162:165], v[194:197], v[82:85]
	v_mfma_f32_16x16x32_bf16 v[78:81], v[154:157], v[202:205], v[78:81]
	v_mfma_f32_16x16x32_bf16 v[74:77], v[162:165], v[202:205], v[74:77]
	v_mfma_f32_16x16x32_bf16 v[70:73], v[154:157], v[210:213], v[70:73]
	v_mfma_f32_16x16x32_bf16 v[66:69], v[162:165], v[210:213], v[66:69]
	s_setprio 0
	s_setprio 1
	v_mfma_f32_16x16x32_bf16 v[30:33], v[166:169], v[182:185], v[30:33]
	v_mfma_f32_16x16x32_bf16 v[26:29], v[174:177], v[182:185], v[26:29]
	v_mfma_f32_16x16x32_bf16 v[22:25], v[166:169], v[190:193], v[22:25]
	v_mfma_f32_16x16x32_bf16 v[18:21], v[174:177], v[190:193], v[18:21]
	v_mfma_f32_16x16x32_bf16 v[14:17], v[166:169], v[198:201], v[14:17]
	v_mfma_f32_16x16x32_bf16 v[10:13], v[174:177], v[198:201], v[10:13]
	v_mfma_f32_16x16x32_bf16 v[6:9], v[166:169], v[206:209], v[6:9]
	v_mfma_f32_16x16x32_bf16 v[2:5], v[174:177], v[206:209], v[2:5]
	v_mfma_f32_16x16x32_bf16 v[30:33], v[170:173], v[186:189], v[30:33]
	v_mfma_f32_16x16x32_bf16 v[26:29], v[178:181], v[186:189], v[26:29]
	v_mfma_f32_16x16x32_bf16 v[22:25], v[170:173], v[194:197], v[22:25]
	v_mfma_f32_16x16x32_bf16 v[18:21], v[178:181], v[194:197], v[18:21]
	v_mfma_f32_16x16x32_bf16 v[14:17], v[170:173], v[202:205], v[14:17]
	v_mfma_f32_16x16x32_bf16 v[10:13], v[178:181], v[202:205], v[10:13]
	v_mfma_f32_16x16x32_bf16 v[6:9], v[170:173], v[210:213], v[6:9]
	v_mfma_f32_16x16x32_bf16 v[2:5], v[178:181], v[210:213], v[2:5]
	s_setprio 0
	s_barrier
	s_add_u32 s60, s60, 0x100
	s_addc_u32 s61, s61, 0
	s_add_u32 s80, s80, 0x100
	s_addc_u32 s81, s81, 0
	s_cmp_gt_u32 s82, 5
	s_mov_b32 s62, s82
	s_cbranch_scc0 .LBB0_861
	v_mov_b32_e32 v252, 0xbdd2d3e7
	s_and_b64 vcc, exec, s[54:55]
	s_cbranch_vccz .LBB0_864
	s_barrier
.LBB0_864:
	s_mul_i32 s5, s74, -9
	s_add_i32 s5, s5, s75
	s_lshl_b32 s60, s74, 4
	v_mov_b32_e32 v138, v148
	v_mov_b32_e32 v144, v1
	s_lshl_b32 s5, s5, 8
	s_ashr_i32 s61, s60, 31
	s_add_i32 s5, s5, s51
	s_lshl_b64 s[60:61], s[60:61], 1
	v_add_u32_e32 v154, s5, v138
	s_add_u32 s60, s69, s60
	v_lshlrev_b32_e32 v138, 4, v144
	s_addc_u32 s61, s70, s61
	v_and_b32_e32 v138, 16, v138
	v_lshl_add_u32 v153, v144, 3, s66
	v_lshl_add_u64 v[144:145], s[60:61], 0, v[138:139]
	v_mul_hi_i32 v138, v154, s49
	v_lshrrev_b32_e32 v155, 31, v138
	v_ashrrev_i32_e32 v138, 5, v138
	v_add_u32_e32 v138, v138, v155
	v_mul_f32_e32 v155, v126, v126
	v_fmaak_f32 v155, v252, v155, 0xc0135761
	v_mul_f32_e32 v156, v122, v122
	v_mul_f32_e32 v155, v126, v155
	v_fmaak_f32 v156, v252, v156, 0xc0135761
	v_mul_f32_e32 v156, v122, v156
	v_exp_f32_e32 v155, v155
	v_exp_f32_e32 v157, v156
	v_mul_f32_e32 v158, v123, v123
	v_add_f32_e32 v155, 1.0, v155
	v_rcp_f32_e32 v156, v155
	v_add_f32_e32 v155, 1.0, v157
	v_mul_f32_e32 v157, v127, v127
	v_fmaak_f32 v157, v252, v157, 0xc0135761
	v_mul_f32_e32 v157, v127, v157
	v_fmaak_f32 v158, v252, v158, 0xc0135761
	v_mul_f32_e32 v158, v123, v158
	v_exp_f32_e32 v157, v157
	v_exp_f32_e32 v159, v158
	v_rcp_f32_e32 v158, v155
	v_add_f32_e32 v155, 1.0, v157
	v_rcp_f32_e32 v157, v155
	v_add_f32_e32 v155, 1.0, v159
	v_mul_f32_e32 v159, v128, v128
	v_fmaak_f32 v159, v252, v159, 0xc0135761
	v_mul_f32_e32 v159, v128, v159
	v_exp_f32_e32 v160, v159
	v_mul_f32_e32 v159, v124, v124
	v_fmaak_f32 v159, v252, v159, 0xc0135761
	v_mul_f32_e32 v159, v124, v159
	v_exp_f32_e32 v161, v159
	v_rcp_f32_e32 v159, v155
	v_add_f32_e32 v155, 1.0, v160
	v_rcp_f32_e32 v160, v155
	v_add_f32_e32 v155, 1.0, v161
	v_mul_f32_e32 v161, v129, v129
	v_fmaak_f32 v161, v252, v161, 0xc0135761
	v_mul_f32_e32 v162, v125, v125
	v_mul_f32_e32 v161, v129, v161
; __device__ __forceinline__ void store8(bf16_t* p, const f32x4& a, const f32x4& b) { u32x4 w; w.x = pk2(a[0], a[1]); w.y = pk2(a[2], a[3]); w.z = pk2(b[0], b[1]); w.w = pk2(b[2], b[3]); *(u32x4*)p = w; }
; __device__ __forceinline__ float gelu_t(float x) { const float u = x + 0.044715f * x * x * x; return x * __builtin_amdgcn_rcpf(1.f + __builtin_amdgcn_exp2f(-2.302208198f * u)); }
;     __device__ __forceinline__ void operator()(const f32x4 (&acc)[2][2][4][2], const pg8::Unit& u, int wr, int wc, int fr, int fq, int buf) const {
;     ...
;             bf16_t* G = (bf16_t*)(ws + R_G); const int g = u.pn, j9 = u.pm - 9 * g;
; #pragma unroll
;             for (int bj = 0; bj < 2; ++bj) { const int n0 = bj * 128 + wc * 32 + 8 * fq, t = n0 >> 4, h0 = n0 & 15;
; #pragma unroll
;                 for (int ai = 0; ai < 2; ++ai)
; #pragma unroll
;                     for (int m = 0; m < 4; ++m) { const int cr = j9 * 256 + ai * 128 + m * 16 + rloc0, b = cr / 144, c = cr - b * 144;
;                         f32x4 v0 = acc[ai][bj][m][0], v1 = acc[ai][bj][m][1];
; #pragma unroll
;                         for (int q = 0; q < 4; ++q) { v0[q] = gelu_t(v0[q]); v1[q] = gelu_t(v1[q]); }
;                         store8(G + ((size_t)b * RB + 16 * c + t) * 512 + 16 * g + h0, v0, v1); } }
	v_fmaak_f32 v162, v252, v162, 0xc0135761
	v_mul_f32_e32 v162, v125, v162
	v_exp_f32_e32 v161, v161
	v_exp_f32_e32 v163, v162
	v_rcp_f32_e32 v162, v155
	v_add_f32_e32 v155, 1.0, v161
	v_rcp_f32_e32 v161, v155
	v_add_f32_e32 v155, 1.0, v163
	v_mul_lo_u32 v164, v138, s72
	v_rcp_f32_e32 v163, v155
	v_pk_mul_f32 v[126:127], v[126:127], v[156:157]
	v_pk_mul_f32 v[156:157], v[122:123], v[158:159]
	v_add_lshl_u32 v122, v164, v154, 4
	v_ashrrev_i32_e32 v146, 4, v153
	v_ashrrev_i32_e32 v123, 31, v122
	v_ashrrev_i32_e32 v147, 31, v146
	v_mad_i64_i32 v[122:123], s[60:61], v138, s73, v[122:123]
	v_pk_mul_f32 v[158:159], v[124:125], v[162:163]
	v_lshl_add_u64 v[124:125], v[122:123], 0, v[146:147]
	v_pk_mul_f32 v[128:129], v[128:129], v[160:161]
	v_lshlrev_b64 v[124:125], 10, v[124:125]
	v_lshl_add_u64 v[160:161], v[144:145], 0, v[124:125]
	v_cvt_pk_bf16_f32 v124, v126, v127
	v_cvt_pk_bf16_f32 v125, v128, v129
	v_cvt_pk_bf16_f32 v126, v156, v157
	v_cvt_pk_bf16_f32 v127, v158, v159
	global_store_dwordx4 v[160:161], v[124:127], off
	v_add_u32_e32 v138, 16, v154
	v_mul_f32_e32 v156, v121, v121
	v_mul_f32_e32 v126, v119, v119
	v_mul_hi_i32 v124, v138, s49
	v_fmaak_f32 v126, v252, v126, 0xc0135761
	v_lshrrev_b32_e32 v125, 31, v124
	v_ashrrev_i32_e32 v124, 5, v124
	v_mul_f32_e32 v126, v119, v126
	v_add_u32_e32 v155, v124, v125
	v_mul_f32_e32 v125, v114, v114
	v_fmaak_f32 v125, v252, v125, 0xc0135761
	v_exp_f32_e32 v127, v126
	v_mul_f32_e32 v126, v115, v115
	v_mul_f32_e32 v125, v114, v125
	v_fmaak_f32 v126, v252, v126, 0xc0135761
	v_mul_f32_e32 v126, v115, v126
	v_exp_f32_e32 v125, v125
	v_mul_f32_e32 v124, v118, v118
	v_exp_f32_e32 v128, v126
	v_fmaak_f32 v156, v252, v156, 0xc0135761
	v_fmaak_f32 v124, v252, v124, 0xc0135761
	v_mul_f32_e32 v156, v121, v156
	v_mul_f32_e32 v124, v118, v124
	v_mul_f32_e32 v129, v116, v116
	v_add_f32_e32 v125, 1.0, v125
	v_fmaak_f32 v129, v252, v129, 0xc0135761
	v_exp_f32_e32 v157, v156
	v_mul_f32_e32 v156, v117, v117
	v_exp_f32_e32 v124, v124
	v_rcp_f32_e32 v126, v125
	v_add_f32_e32 v125, 1.0, v127
	v_add_f32_e32 v127, 1.0, v128
	v_mul_f32_e32 v128, v120, v120
	v_mul_f32_e32 v129, v116, v129
	v_fmaak_f32 v156, v252, v156, 0xc0135761
	v_fmaak_f32 v128, v252, v128, 0xc0135761
	v_mul_f32_e32 v156, v117, v156
	v_mul_f32_e32 v128, v120, v128
	v_exp_f32_e32 v129, v129
	v_exp_f32_e32 v159, v156
	v_add_f32_e32 v124, 1.0, v124
	v_exp_f32_e32 v128, v128
	v_rcp_f32_e32 v124, v124
	v_rcp_f32_e32 v125, v125
	v_rcp_f32_e32 v127, v127
	v_add_f32_e32 v129, 1.0, v129
	v_rcp_f32_e32 v156, v129
	v_add_f32_e32 v129, 1.0, v157
	v_add_f32_e32 v157, 1.0, v159
	v_mul_lo_u32 v158, v155, s72
	v_add_f32_e32 v128, 1.0, v128
	v_rcp_f32_e32 v157, v157
	v_rcp_f32_e32 v128, v128
	v_rcp_f32_e32 v129, v129
	v_pk_mul_f32 v[118:119], v[118:119], v[124:125]
	v_pk_mul_f32 v[124:125], v[114:115], v[126:127]
	v_add_lshl_u32 v114, v158, v138, 4
	v_ashrrev_i32_e32 v115, 31, v114
	v_mad_i64_i32 v[114:115], s[60:61], v155, s73, v[114:115]
	v_pk_mul_f32 v[126:127], v[116:117], v[156:157]
	v_lshl_add_u64 v[116:117], v[114:115], 0, v[146:147]
	v_pk_mul_f32 v[120:121], v[120:121], v[128:129]
	v_lshlrev_b64 v[116:117], 10, v[116:117]
	v_lshl_add_u64 v[128:129], v[144:145], 0, v[116:117]
	v_cvt_pk_bf16_f32 v116, v118, v119
	v_cvt_pk_bf16_f32 v117, v120, v121
	v_cvt_pk_bf16_f32 v118, v124, v125
	v_cvt_pk_bf16_f32 v119, v126, v127
	global_store_dwordx4 v[128:129], v[116:119], off
	v_add_u32_e32 v126, 32, v154
	v_mul_f32_e32 v124, v113, v113
	v_mul_f32_e32 v118, v111, v111
	v_mul_hi_i32 v116, v126, s49
	v_fmaak_f32 v118, v252, v118, 0xc0135761
	v_lshrrev_b32_e32 v117, 31, v116
	v_ashrrev_i32_e32 v116, 5, v116
	v_mul_f32_e32 v118, v111, v118
	v_add_u32_e32 v127, v116, v117
	v_mul_f32_e32 v117, v106, v106
	v_fmaak_f32 v117, v252, v117, 0xc0135761
	v_exp_f32_e32 v119, v118
	v_mul_f32_e32 v118, v107, v107
	v_mul_f32_e32 v117, v106, v117
	v_fmaak_f32 v118, v252, v118, 0xc0135761
	v_mul_f32_e32 v118, v107, v118
	v_exp_f32_e32 v117, v117
	v_mul_f32_e32 v116, v110, v110
	v_exp_f32_e32 v120, v118
	v_fmaak_f32 v124, v252, v124, 0xc0135761
	v_fmaak_f32 v116, v252, v116, 0xc0135761
	v_mul_f32_e32 v124, v113, v124
	v_mul_f32_e32 v116, v110, v116
	v_mul_f32_e32 v121, v108, v108
	v_add_f32_e32 v117, 1.0, v117
	v_fmaak_f32 v121, v252, v121, 0xc0135761
	v_exp_f32_e32 v125, v124
	v_mul_f32_e32 v124, v109, v109
	v_exp_f32_e32 v116, v116
	v_rcp_f32_e32 v118, v117
	v_add_f32_e32 v117, 1.0, v119
	v_add_f32_e32 v119, 1.0, v120
	v_mul_f32_e32 v120, v112, v112
	v_mul_f32_e32 v121, v108, v121
	v_fmaak_f32 v124, v252, v124, 0xc0135761
	v_fmaak_f32 v120, v252, v120, 0xc0135761
	v_mul_f32_e32 v124, v109, v124
	v_mul_f32_e32 v120, v112, v120
	v_exp_f32_e32 v121, v121
	v_exp_f32_e32 v129, v124
	v_add_f32_e32 v116, 1.0, v116
	v_exp_f32_e32 v120, v120
	v_rcp_f32_e32 v116, v116
	v_rcp_f32_e32 v117, v117
	v_rcp_f32_e32 v119, v119
	v_add_f32_e32 v121, 1.0, v121
	v_rcp_f32_e32 v124, v121
	v_add_f32_e32 v121, 1.0, v125
	v_add_f32_e32 v125, 1.0, v129
	v_mul_lo_u32 v128, v127, s72
	v_add_f32_e32 v120, 1.0, v120
	v_rcp_f32_e32 v125, v125
	v_rcp_f32_e32 v120, v120
	v_rcp_f32_e32 v121, v121
	v_pk_mul_f32 v[110:111], v[110:111], v[116:117]
	v_pk_mul_f32 v[116:117], v[106:107], v[118:119]
	v_add_lshl_u32 v106, v128, v126, 4
	v_ashrrev_i32_e32 v107, 31, v106
	v_mad_i64_i32 v[106:107], s[60:61], v127, s73, v[106:107]
	v_pk_mul_f32 v[118:119], v[108:109], v[124:125]
	v_lshl_add_u64 v[108:109], v[106:107], 0, v[146:147]
	v_pk_mul_f32 v[112:113], v[112:113], v[120:121]
	v_lshlrev_b64 v[108:109], 10, v[108:109]
	v_lshl_add_u64 v[120:121], v[144:145], 0, v[108:109]
	v_cvt_pk_bf16_f32 v108, v110, v111
	v_cvt_pk_bf16_f32 v109, v112, v113
; __device__ __forceinline__ void store8(bf16_t* p, const f32x4& a, const f32x4& b) { u32x4 w; w.x = pk2(a[0], a[1]); w.y = pk2(a[2], a[3]); w.z = pk2(b[0], b[1]); w.w = pk2(b[2], b[3]); *(u32x4*)p = w; }
; __device__ __forceinline__ float gelu_t(float x) { const float u = x + 0.044715f * x * x * x; return x * __builtin_amdgcn_rcpf(1.f + __builtin_amdgcn_exp2f(-2.302208198f * u)); }
;     __device__ __forceinline__ void operator()(const f32x4 (&acc)[2][2][4][2], const pg8::Unit& u, int wr, int wc, int fr, int fq, int buf) const {
;     ...
;                     for (int m = 0; m < 4; ++m) { const int cr = j9 * 256 + ai * 128 + m * 16 + rloc0, b = cr / 144, c = cr - b * 144;
;                         f32x4 v0 = acc[ai][bj][m][0], v1 = acc[ai][bj][m][1];
; #pragma unroll
;                         for (int q = 0; q < 4; ++q) { v0[q] = gelu_t(v0[q]); v1[q] = gelu_t(v1[q]); }
;                         store8(G + ((size_t)b * RB + 16 * c + t) * 512 + 16 * g + h0, v0, v1); } }
	v_cvt_pk_bf16_f32 v110, v116, v117
	v_cvt_pk_bf16_f32 v111, v118, v119
	global_store_dwordx4 v[120:121], v[108:111], off
	v_add_u32_e32 v118, 48, v154
	v_mul_f32_e32 v116, v105, v105
	v_mul_f32_e32 v110, v103, v103
	v_mul_hi_i32 v108, v118, s49
	v_fmaak_f32 v110, v252, v110, 0xc0135761
	v_lshrrev_b32_e32 v109, 31, v108
	v_ashrrev_i32_e32 v108, 5, v108
	v_mul_f32_e32 v110, v103, v110
	v_add_u32_e32 v119, v108, v109
	v_mul_f32_e32 v109, v98, v98
	v_fmaak_f32 v109, v252, v109, 0xc0135761
	v_exp_f32_e32 v111, v110
	v_mul_f32_e32 v110, v99, v99
	v_mul_f32_e32 v109, v98, v109
	v_fmaak_f32 v110, v252, v110, 0xc0135761
	v_mul_f32_e32 v110, v99, v110
	v_exp_f32_e32 v109, v109
	v_mul_f32_e32 v108, v102, v102
	v_exp_f32_e32 v112, v110
	v_fmaak_f32 v116, v252, v116, 0xc0135761
	v_fmaak_f32 v108, v252, v108, 0xc0135761
	v_mul_f32_e32 v116, v105, v116
	v_mul_f32_e32 v108, v102, v108
	v_mul_f32_e32 v113, v100, v100
	v_add_f32_e32 v109, 1.0, v109
	v_fmaak_f32 v113, v252, v113, 0xc0135761
	v_exp_f32_e32 v117, v116
	v_mul_f32_e32 v116, v101, v101
	v_exp_f32_e32 v108, v108
	v_rcp_f32_e32 v110, v109
	v_add_f32_e32 v109, 1.0, v111
	v_add_f32_e32 v111, 1.0, v112
	v_mul_f32_e32 v112, v104, v104
	v_mul_f32_e32 v113, v100, v113
	v_fmaak_f32 v116, v252, v116, 0xc0135761
	v_fmaak_f32 v112, v252, v112, 0xc0135761
	v_mul_f32_e32 v116, v101, v116
	v_mul_f32_e32 v112, v104, v112
	v_exp_f32_e32 v113, v113
	v_exp_f32_e32 v121, v116
	v_add_f32_e32 v108, 1.0, v108
	v_exp_f32_e32 v112, v112
	v_rcp_f32_e32 v108, v108
	v_rcp_f32_e32 v109, v109
	v_rcp_f32_e32 v111, v111
	v_add_f32_e32 v113, 1.0, v113
	v_rcp_f32_e32 v116, v113
	v_add_f32_e32 v113, 1.0, v117
	v_add_f32_e32 v117, 1.0, v121
	v_mul_lo_u32 v120, v119, s72
	v_add_f32_e32 v112, 1.0, v112
	v_rcp_f32_e32 v117, v117
	v_rcp_f32_e32 v112, v112
	v_rcp_f32_e32 v113, v113
	v_pk_mul_f32 v[102:103], v[102:103], v[108:109]
	v_pk_mul_f32 v[108:109], v[98:99], v[110:111]
	v_add_lshl_u32 v98, v120, v118, 4
	v_ashrrev_i32_e32 v99, 31, v98
	v_mad_i64_i32 v[98:99], s[60:61], v119, s73, v[98:99]
	v_pk_mul_f32 v[110:111], v[100:101], v[116:117]
	v_lshl_add_u64 v[100:101], v[98:99], 0, v[146:147]
	v_pk_mul_f32 v[104:105], v[104:105], v[112:113]
	v_lshlrev_b64 v[100:101], 10, v[100:101]
	v_lshl_add_u64 v[112:113], v[144:145], 0, v[100:101]
	v_cvt_pk_bf16_f32 v100, v102, v103
	v_cvt_pk_bf16_f32 v101, v104, v105
	v_cvt_pk_bf16_f32 v102, v108, v109
	v_cvt_pk_bf16_f32 v103, v110, v111
	global_store_dwordx4 v[112:113], v[100:103], off
	v_add_u32_e32 v110, 0x80, v154
	v_mul_f32_e32 v108, v97, v97
	v_mul_f32_e32 v102, v95, v95
	v_mul_hi_i32 v100, v110, s49
	v_fmaak_f32 v102, v252, v102, 0xc0135761
	v_lshrrev_b32_e32 v101, 31, v100
	v_ashrrev_i32_e32 v100, 5, v100
	v_mul_f32_e32 v102, v95, v102
	v_add_u32_e32 v111, v100, v101
	v_mul_f32_e32 v101, v90, v90
	v_fmaak_f32 v101, v252, v101, 0xc0135761
	v_exp_f32_e32 v103, v102
	v_mul_f32_e32 v102, v91, v91
	v_mul_f32_e32 v101, v90, v101
	v_fmaak_f32 v102, v252, v102, 0xc0135761
	v_mul_f32_e32 v102, v91, v102
	v_exp_f32_e32 v101, v101
	v_mul_f32_e32 v100, v94, v94
	v_exp_f32_e32 v104, v102
	v_fmaak_f32 v108, v252, v108, 0xc0135761
	v_fmaak_f32 v100, v252, v100, 0xc0135761
	v_mul_f32_e32 v108, v97, v108
	v_mul_f32_e32 v100, v94, v100
	v_mul_f32_e32 v105, v92, v92
	v_add_f32_e32 v101, 1.0, v101
	v_fmaak_f32 v105, v252, v105, 0xc0135761
	v_exp_f32_e32 v109, v108
	v_mul_f32_e32 v108, v93, v93
	v_exp_f32_e32 v100, v100
	v_rcp_f32_e32 v102, v101
	v_add_f32_e32 v101, 1.0, v103
	v_add_f32_e32 v103, 1.0, v104
	v_mul_f32_e32 v104, v96, v96
	v_mul_f32_e32 v105, v92, v105
	v_fmaak_f32 v108, v252, v108, 0xc0135761
	v_fmaak_f32 v104, v252, v104, 0xc0135761
	v_mul_f32_e32 v108, v93, v108
	v_mul_f32_e32 v104, v96, v104
	v_exp_f32_e32 v105, v105
	v_exp_f32_e32 v113, v108
	v_add_f32_e32 v100, 1.0, v100
	v_exp_f32_e32 v104, v104
	v_rcp_f32_e32 v100, v100
	v_rcp_f32_e32 v101, v101
	v_rcp_f32_e32 v103, v103
	v_add_f32_e32 v105, 1.0, v105
	v_rcp_f32_e32 v108, v105
	v_add_f32_e32 v105, 1.0, v109
	v_add_f32_e32 v109, 1.0, v113
	v_mul_lo_u32 v112, v111, s72
	v_add_f32_e32 v104, 1.0, v104
	v_rcp_f32_e32 v109, v109
	v_rcp_f32_e32 v104, v104
	v_rcp_f32_e32 v105, v105
	v_pk_mul_f32 v[94:95], v[94:95], v[100:101]
	v_pk_mul_f32 v[100:101], v[90:91], v[102:103]
	v_add_lshl_u32 v90, v112, v110, 4
	v_ashrrev_i32_e32 v91, 31, v90
	v_mad_i64_i32 v[90:91], s[60:61], v111, s73, v[90:91]
	v_pk_mul_f32 v[102:103], v[92:93], v[108:109]
	v_lshl_add_u64 v[92:93], v[90:91], 0, v[146:147]
	v_pk_mul_f32 v[96:97], v[96:97], v[104:105]
	v_lshlrev_b64 v[92:93], 10, v[92:93]
	v_lshl_add_u64 v[104:105], v[144:145], 0, v[92:93]
	v_cvt_pk_bf16_f32 v92, v94, v95
	v_cvt_pk_bf16_f32 v93, v96, v97
	v_cvt_pk_bf16_f32 v94, v100, v101
	v_cvt_pk_bf16_f32 v95, v102, v103
	global_store_dwordx4 v[104:105], v[92:95], off
	v_add_u32_e32 v102, 0x90, v154
	v_mul_f32_e32 v100, v89, v89
	v_mul_f32_e32 v94, v87, v87
	v_mul_hi_i32 v92, v102, s49
	v_fmaak_f32 v94, v252, v94, 0xc0135761
	v_lshrrev_b32_e32 v93, 31, v92
	v_ashrrev_i32_e32 v92, 5, v92
	v_mul_f32_e32 v94, v87, v94
	v_add_u32_e32 v103, v92, v93
	v_mul_f32_e32 v93, v82, v82
	v_fmaak_f32 v93, v252, v93, 0xc0135761
	v_exp_f32_e32 v95, v94
	v_mul_f32_e32 v94, v83, v83
	v_mul_f32_e32 v93, v82, v93
	v_fmaak_f32 v94, v252, v94, 0xc0135761
	v_mul_f32_e32 v94, v83, v94
	v_exp_f32_e32 v93, v93
	v_mul_f32_e32 v92, v86, v86
	v_exp_f32_e32 v96, v94
	v_fmaak_f32 v100, v252, v100, 0xc0135761
	v_fmaak_f32 v92, v252, v92, 0xc0135761
	v_mul_f32_e32 v100, v89, v100
	v_mul_f32_e32 v92, v86, v92
	v_mul_f32_e32 v97, v84, v84
	v_add_f32_e32 v93, 1.0, v93
	v_fmaak_f32 v97, v252, v97, 0xc0135761
	v_exp_f32_e32 v101, v100
; __device__ __forceinline__ void store8(bf16_t* p, const f32x4& a, const f32x4& b) { u32x4 w; w.x = pk2(a[0], a[1]); w.y = pk2(a[2], a[3]); w.z = pk2(b[0], b[1]); w.w = pk2(b[2], b[3]); *(u32x4*)p = w; }
; __device__ __forceinline__ float gelu_t(float x) { const float u = x + 0.044715f * x * x * x; return x * __builtin_amdgcn_rcpf(1.f + __builtin_amdgcn_exp2f(-2.302208198f * u)); }
;     __device__ __forceinline__ void operator()(const f32x4 (&acc)[2][2][4][2], const pg8::Unit& u, int wr, int wc, int fr, int fq, int buf) const {
;     ...
;                     for (int m = 0; m < 4; ++m) { const int cr = j9 * 256 + ai * 128 + m * 16 + rloc0, b = cr / 144, c = cr - b * 144;
;                         f32x4 v0 = acc[ai][bj][m][0], v1 = acc[ai][bj][m][1];
; #pragma unroll
;                         for (int q = 0; q < 4; ++q) { v0[q] = gelu_t(v0[q]); v1[q] = gelu_t(v1[q]); }
;                         store8(G + ((size_t)b * RB + 16 * c + t) * 512 + 16 * g + h0, v0, v1); } }
	v_mul_f32_e32 v100, v85, v85
	v_exp_f32_e32 v92, v92
	v_rcp_f32_e32 v94, v93
	v_add_f32_e32 v93, 1.0, v95
	v_add_f32_e32 v95, 1.0, v96
	v_mul_f32_e32 v96, v88, v88
	v_mul_f32_e32 v97, v84, v97
	v_fmaak_f32 v100, v252, v100, 0xc0135761
	v_fmaak_f32 v96, v252, v96, 0xc0135761
	v_mul_f32_e32 v100, v85, v100
	v_mul_f32_e32 v96, v88, v96
	v_exp_f32_e32 v97, v97
	v_exp_f32_e32 v105, v100
	v_add_f32_e32 v92, 1.0, v92
	v_exp_f32_e32 v96, v96
	v_rcp_f32_e32 v92, v92
	v_rcp_f32_e32 v93, v93
	v_rcp_f32_e32 v95, v95
	v_add_f32_e32 v97, 1.0, v97
	v_rcp_f32_e32 v100, v97
	v_add_f32_e32 v97, 1.0, v101
	v_add_f32_e32 v101, 1.0, v105
	v_mul_lo_u32 v104, v103, s72
	v_add_f32_e32 v96, 1.0, v96
	v_rcp_f32_e32 v101, v101
	v_rcp_f32_e32 v96, v96
	v_rcp_f32_e32 v97, v97
	v_pk_mul_f32 v[86:87], v[86:87], v[92:93]
	v_pk_mul_f32 v[92:93], v[82:83], v[94:95]
	v_add_lshl_u32 v82, v104, v102, 4
	v_ashrrev_i32_e32 v83, 31, v82
	v_mad_i64_i32 v[82:83], s[60:61], v103, s73, v[82:83]
	v_pk_mul_f32 v[94:95], v[84:85], v[100:101]
	v_lshl_add_u64 v[84:85], v[82:83], 0, v[146:147]
	v_pk_mul_f32 v[88:89], v[88:89], v[96:97]
	v_lshlrev_b64 v[84:85], 10, v[84:85]
	v_lshl_add_u64 v[96:97], v[144:145], 0, v[84:85]
	v_cvt_pk_bf16_f32 v84, v86, v87
	v_cvt_pk_bf16_f32 v85, v88, v89
	v_cvt_pk_bf16_f32 v86, v92, v93
	v_cvt_pk_bf16_f32 v87, v94, v95
	global_store_dwordx4 v[96:97], v[84:87], off
	v_add_u32_e32 v94, 0xa0, v154
	v_mul_f32_e32 v92, v81, v81
	v_mul_f32_e32 v86, v79, v79
	v_mul_hi_i32 v84, v94, s49
	v_fmaak_f32 v86, v252, v86, 0xc0135761
	v_lshrrev_b32_e32 v85, 31, v84
	v_ashrrev_i32_e32 v84, 5, v84
	v_mul_f32_e32 v86, v79, v86
	v_add_u32_e32 v95, v84, v85
	v_mul_f32_e32 v85, v74, v74
	v_fmaak_f32 v85, v252, v85, 0xc0135761
	v_exp_f32_e32 v87, v86
	v_mul_f32_e32 v86, v75, v75
	v_mul_f32_e32 v85, v74, v85
	v_fmaak_f32 v86, v252, v86, 0xc0135761
	v_mul_f32_e32 v86, v75, v86
	v_exp_f32_e32 v85, v85
	v_mul_f32_e32 v84, v78, v78
	v_exp_f32_e32 v88, v86
	v_fmaak_f32 v92, v252, v92, 0xc0135761
	v_fmaak_f32 v84, v252, v84, 0xc0135761
	v_mul_f32_e32 v92, v81, v92
	v_mul_f32_e32 v84, v78, v84
	v_mul_f32_e32 v89, v76, v76
	v_add_f32_e32 v85, 1.0, v85
	v_fmaak_f32 v89, v252, v89, 0xc0135761
	v_exp_f32_e32 v93, v92
	v_mul_f32_e32 v92, v77, v77
	v_exp_f32_e32 v84, v84
	v_rcp_f32_e32 v86, v85
	v_add_f32_e32 v85, 1.0, v87
	v_add_f32_e32 v87, 1.0, v88
	v_mul_f32_e32 v88, v80, v80
	v_mul_f32_e32 v89, v76, v89
	v_fmaak_f32 v92, v252, v92, 0xc0135761
	v_fmaak_f32 v88, v252, v88, 0xc0135761
	v_mul_f32_e32 v92, v77, v92
	v_mul_f32_e32 v88, v80, v88
	v_exp_f32_e32 v89, v89
	v_exp_f32_e32 v97, v92
	v_add_f32_e32 v84, 1.0, v84
	v_exp_f32_e32 v88, v88
	v_rcp_f32_e32 v84, v84
	v_rcp_f32_e32 v85, v85
	v_rcp_f32_e32 v87, v87
	v_add_f32_e32 v89, 1.0, v89
	v_rcp_f32_e32 v92, v89
	v_add_f32_e32 v89, 1.0, v93
	v_add_f32_e32 v93, 1.0, v97
	v_mul_lo_u32 v96, v95, s72
	v_add_f32_e32 v88, 1.0, v88
	v_rcp_f32_e32 v93, v93
	v_rcp_f32_e32 v88, v88
	v_rcp_f32_e32 v89, v89
	v_pk_mul_f32 v[78:79], v[78:79], v[84:85]
	v_pk_mul_f32 v[84:85], v[74:75], v[86:87]
	v_add_lshl_u32 v74, v96, v94, 4
	v_ashrrev_i32_e32 v75, 31, v74
	v_mad_i64_i32 v[74:75], s[60:61], v95, s73, v[74:75]
	v_pk_mul_f32 v[86:87], v[76:77], v[92:93]
	v_lshl_add_u64 v[76:77], v[74:75], 0, v[146:147]
	v_pk_mul_f32 v[80:81], v[80:81], v[88:89]
	v_lshlrev_b64 v[76:77], 10, v[76:77]
	v_lshl_add_u64 v[88:89], v[144:145], 0, v[76:77]
	v_cvt_pk_bf16_f32 v76, v78, v79
	v_cvt_pk_bf16_f32 v77, v80, v81
	v_cvt_pk_bf16_f32 v78, v84, v85
	v_cvt_pk_bf16_f32 v79, v86, v87
	global_store_dwordx4 v[88:89], v[76:79], off
	v_add_u32_e32 v86, 0xb0, v154
	v_mul_f32_e32 v84, v73, v73
	v_mul_f32_e32 v78, v71, v71
	v_mul_hi_i32 v76, v86, s49
	v_fmaak_f32 v78, v252, v78, 0xc0135761
	v_lshrrev_b32_e32 v77, 31, v76
	v_ashrrev_i32_e32 v76, 5, v76
	v_mul_f32_e32 v78, v71, v78
	v_add_u32_e32 v87, v76, v77
	v_mul_f32_e32 v77, v66, v66
	v_fmaak_f32 v77, v252, v77, 0xc0135761
	v_exp_f32_e32 v79, v78
	v_mul_f32_e32 v78, v67, v67
	v_mul_f32_e32 v77, v66, v77
	v_fmaak_f32 v78, v252, v78, 0xc0135761
	v_mul_f32_e32 v78, v67, v78
	v_exp_f32_e32 v77, v77
	v_mul_f32_e32 v76, v70, v70
	v_exp_f32_e32 v80, v78
	v_fmaak_f32 v84, v252, v84, 0xc0135761
	v_fmaak_f32 v76, v252, v76, 0xc0135761
	v_mul_f32_e32 v84, v73, v84
	v_mul_f32_e32 v76, v70, v76
	v_mul_f32_e32 v81, v68, v68
	v_add_f32_e32 v77, 1.0, v77
	v_fmaak_f32 v81, v252, v81, 0xc0135761
	v_exp_f32_e32 v85, v84
	v_mul_f32_e32 v84, v69, v69
	v_exp_f32_e32 v76, v76
	v_rcp_f32_e32 v78, v77
	v_add_f32_e32 v77, 1.0, v79
	v_add_f32_e32 v79, 1.0, v80
	v_mul_f32_e32 v80, v72, v72
	v_mul_f32_e32 v81, v68, v81
	v_fmaak_f32 v84, v252, v84, 0xc0135761
	v_fmaak_f32 v80, v252, v80, 0xc0135761
	v_mul_f32_e32 v84, v69, v84
	v_mul_f32_e32 v80, v72, v80
	v_exp_f32_e32 v81, v81
	v_exp_f32_e32 v89, v84
	v_add_f32_e32 v76, 1.0, v76
	v_exp_f32_e32 v80, v80
	v_rcp_f32_e32 v76, v76
	v_rcp_f32_e32 v77, v77
	v_rcp_f32_e32 v79, v79
	v_add_f32_e32 v81, 1.0, v81
	v_rcp_f32_e32 v84, v81
	v_add_f32_e32 v81, 1.0, v85
	v_add_f32_e32 v85, 1.0, v89
	v_mul_lo_u32 v88, v87, s72
	v_add_f32_e32 v80, 1.0, v80
	v_rcp_f32_e32 v85, v85
	v_rcp_f32_e32 v80, v80
	v_rcp_f32_e32 v81, v81
	v_pk_mul_f32 v[70:71], v[70:71], v[76:77]
	v_pk_mul_f32 v[76:77], v[66:67], v[78:79]
	v_add_lshl_u32 v66, v88, v86, 4
	v_ashrrev_i32_e32 v67, 31, v66
	v_mad_i64_i32 v[66:67], s[60:61], v87, s73, v[66:67]
	v_pk_mul_f32 v[78:79], v[68:69], v[84:85]
	v_lshl_add_u64 v[68:69], v[66:67], 0, v[146:147]
	v_pk_mul_f32 v[72:73], v[72:73], v[80:81]
	v_lshlrev_b64 v[68:69], 10, v[68:69]
	v_lshl_add_u64 v[80:81], v[144:145], 0, v[68:69]
	v_cvt_pk_bf16_f32 v68, v70, v71
	v_cvt_pk_bf16_f32 v69, v72, v73
; __device__ __forceinline__ void store8(bf16_t* p, const f32x4& a, const f32x4& b) { u32x4 w; w.x = pk2(a[0], a[1]); w.y = pk2(a[2], a[3]); w.z = pk2(b[0], b[1]); w.w = pk2(b[2], b[3]); *(u32x4*)p = w; }
; __device__ __forceinline__ float gelu_t(float x) { const float u = x + 0.044715f * x * x * x; return x * __builtin_amdgcn_rcpf(1.f + __builtin_amdgcn_exp2f(-2.302208198f * u)); }
;     __device__ __forceinline__ void operator()(const f32x4 (&acc)[2][2][4][2], const pg8::Unit& u, int wr, int wc, int fr, int fq, int buf) const {
;     ...
;                     for (int m = 0; m < 4; ++m) { const int cr = j9 * 256 + ai * 128 + m * 16 + rloc0, b = cr / 144, c = cr - b * 144;
;                         f32x4 v0 = acc[ai][bj][m][0], v1 = acc[ai][bj][m][1];
; #pragma unroll
;                         for (int q = 0; q < 4; ++q) { v0[q] = gelu_t(v0[q]); v1[q] = gelu_t(v1[q]); }
;                         store8(G + ((size_t)b * RB + 16 * c + t) * 512 + 16 * g + h0, v0, v1); } }
	v_cvt_pk_bf16_f32 v70, v76, v77
	v_cvt_pk_bf16_f32 v71, v78, v79
	global_store_dwordx4 v[80:81], v[68:71], off
	v_mul_f32_e32 v72, v63, v63
	v_fmaak_f32 v72, v252, v72, 0xc0135761
	v_mul_f32_e32 v69, v62, v62
	v_fmaak_f32 v69, v252, v69, 0xc0135761
	v_mul_f32_e32 v69, v62, v69
	v_mul_f32_e32 v72, v63, v72
	v_exp_f32_e32 v70, v69
	v_mul_f32_e32 v69, v58, v58
	v_fmaak_f32 v69, v252, v69, 0xc0135761
	v_exp_f32_e32 v73, v72
	v_mul_f32_e32 v72, v59, v59
	v_mul_f32_e32 v69, v58, v69
	v_fmaak_f32 v72, v252, v72, 0xc0135761
	v_mul_f32_e32 v72, v59, v72
	v_exp_f32_e32 v71, v69
	v_exp_f32_e32 v76, v72
	v_mul_f32_e32 v78, v65, v65
	v_fmaak_f32 v78, v252, v78, 0xc0135761
	v_mul_f32_e32 v78, v65, v78
	v_add_f32_e32 v71, 1.0, v71
	v_mul_f32_e32 v77, v60, v60
	v_rcp_f32_e32 v72, v71
	v_add_f32_e32 v71, 1.0, v73
	v_add_f32_e32 v73, 1.0, v76
	v_mul_f32_e32 v76, v64, v64
	v_fmaak_f32 v77, v252, v77, 0xc0135761
	v_exp_f32_e32 v79, v78
	v_mul_f32_e32 v78, v61, v61
	v_fmaak_f32 v76, v252, v76, 0xc0135761
	v_mul_f32_e32 v77, v60, v77
	v_fmaak_f32 v78, v252, v78, 0xc0135761
	v_mul_f32_e32 v76, v64, v76
	v_mul_f32_e32 v78, v61, v78
	v_exp_f32_e32 v77, v77
	v_exp_f32_e32 v76, v76
	v_exp_f32_e32 v80, v78
	v_add_f32_e32 v70, 1.0, v70
	v_add_f32_e32 v77, 1.0, v77
	v_rcp_f32_e32 v70, v70
	v_rcp_f32_e32 v71, v71
	v_rcp_f32_e32 v73, v73
	v_add_f32_e32 v76, 1.0, v76
	v_rcp_f32_e32 v78, v77
	v_add_f32_e32 v77, 1.0, v79
	v_add_f32_e32 v79, 1.0, v80
	v_add_u32_e32 v68, 0x80, v153
	v_rcp_f32_e32 v76, v76
	v_rcp_f32_e32 v77, v77
	v_rcp_f32_e32 v79, v79
	v_ashrrev_i32_e32 v68, 4, v68
	v_ashrrev_i32_e32 v69, 31, v68
	v_pk_mul_f32 v[62:63], v[62:63], v[70:71]
	v_pk_mul_f32 v[70:71], v[58:59], v[72:73]
	v_lshl_add_u64 v[58:59], v[122:123], 0, v[68:69]
	v_pk_mul_f32 v[64:65], v[64:65], v[76:77]
	v_pk_mul_f32 v[72:73], v[60:61], v[78:79]
	v_lshlrev_b64 v[58:59], 10, v[58:59]
	v_lshl_add_u64 v[76:77], v[144:145], 0, v[58:59]
	v_cvt_pk_bf16_f32 v58, v62, v63
	v_cvt_pk_bf16_f32 v59, v64, v65
	v_cvt_pk_bf16_f32 v60, v70, v71
	v_cvt_pk_bf16_f32 v61, v72, v73
	v_mul_f32_e32 v62, v54, v54
	global_store_dwordx4 v[76:77], v[58:61], off
	v_fmaak_f32 v62, v252, v62, 0xc0135761
	v_mul_f32_e32 v62, v54, v62
	v_mul_f32_e32 v60, v55, v55
	v_fmaak_f32 v60, v252, v60, 0xc0135761
	v_mul_f32_e32 v60, v55, v60
	v_mul_f32_e32 v63, v50, v50
	v_exp_f32_e32 v62, v62
	v_fmaak_f32 v63, v252, v63, 0xc0135761
	v_exp_f32_e32 v61, v60
	v_mul_f32_e32 v60, v51, v51
	v_mul_f32_e32 v63, v50, v63
	v_fmaak_f32 v60, v252, v60, 0xc0135761
	v_mul_f32_e32 v60, v51, v60
	v_exp_f32_e32 v63, v63
	v_add_f32_e32 v58, 1.0, v62
	v_exp_f32_e32 v62, v60
	v_mul_f32_e32 v64, v57, v57
	v_fmaak_f32 v64, v252, v64, 0xc0135761
	v_mul_f32_e32 v64, v57, v64
	v_add_f32_e32 v59, 1.0, v63
	v_mul_f32_e32 v63, v52, v52
	v_rcp_f32_e32 v60, v59
	v_add_f32_e32 v59, 1.0, v61
	v_add_f32_e32 v61, 1.0, v62
	v_mul_f32_e32 v62, v56, v56
	v_fmaak_f32 v63, v252, v63, 0xc0135761
	v_exp_f32_e32 v65, v64
	v_mul_f32_e32 v64, v53, v53
	v_fmaak_f32 v62, v252, v62, 0xc0135761
	v_mul_f32_e32 v63, v52, v63
	v_fmaak_f32 v64, v252, v64, 0xc0135761
	v_mul_f32_e32 v62, v56, v62
	v_mul_f32_e32 v64, v53, v64
	v_exp_f32_e32 v63, v63
	v_exp_f32_e32 v62, v62
	v_exp_f32_e32 v70, v64
	v_add_f32_e32 v63, 1.0, v63
	v_rcp_f32_e32 v58, v58
	v_rcp_f32_e32 v59, v59
	v_rcp_f32_e32 v61, v61
	v_add_f32_e32 v62, 1.0, v62
	v_rcp_f32_e32 v64, v63
	v_add_f32_e32 v63, 1.0, v65
	v_add_f32_e32 v65, 1.0, v70
	v_rcp_f32_e32 v62, v62
	v_rcp_f32_e32 v63, v63
	v_rcp_f32_e32 v65, v65
	v_pk_mul_f32 v[54:55], v[54:55], v[58:59]
	v_pk_mul_f32 v[58:59], v[50:51], v[60:61]
	v_lshl_add_u64 v[50:51], v[114:115], 0, v[68:69]
	v_pk_mul_f32 v[56:57], v[56:57], v[62:63]
	v_pk_mul_f32 v[60:61], v[52:53], v[64:65]
	v_lshlrev_b64 v[50:51], 10, v[50:51]
	v_lshl_add_u64 v[62:63], v[144:145], 0, v[50:51]
	v_cvt_pk_bf16_f32 v50, v54, v55
	v_cvt_pk_bf16_f32 v51, v56, v57
	v_cvt_pk_bf16_f32 v52, v58, v59
	v_cvt_pk_bf16_f32 v53, v60, v61
	v_mul_f32_e32 v54, v46, v46
	global_store_dwordx4 v[62:63], v[50:53], off
	v_fmaak_f32 v54, v252, v54, 0xc0135761
	v_mul_f32_e32 v54, v46, v54
	v_mul_f32_e32 v52, v47, v47
	v_fmaak_f32 v52, v252, v52, 0xc0135761
	v_mul_f32_e32 v52, v47, v52
	v_mul_f32_e32 v55, v42, v42
	v_exp_f32_e32 v54, v54
	v_fmaak_f32 v55, v252, v55, 0xc0135761
	v_exp_f32_e32 v53, v52
	v_mul_f32_e32 v52, v43, v43
	v_mul_f32_e32 v55, v42, v55
	v_fmaak_f32 v52, v252, v52, 0xc0135761
	v_mul_f32_e32 v52, v43, v52
	v_exp_f32_e32 v55, v55
	v_add_f32_e32 v50, 1.0, v54
	v_exp_f32_e32 v54, v52
	v_mul_f32_e32 v56, v49, v49
	v_fmaak_f32 v56, v252, v56, 0xc0135761
	v_mul_f32_e32 v56, v49, v56
	v_add_f32_e32 v51, 1.0, v55
	v_mul_f32_e32 v55, v44, v44
	v_rcp_f32_e32 v52, v51
	v_add_f32_e32 v51, 1.0, v53
	v_add_f32_e32 v53, 1.0, v54
	v_mul_f32_e32 v54, v48, v48
	v_fmaak_f32 v55, v252, v55, 0xc0135761
	v_exp_f32_e32 v57, v56
	v_mul_f32_e32 v56, v45, v45
	v_fmaak_f32 v54, v252, v54, 0xc0135761
	v_mul_f32_e32 v55, v44, v55
	v_fmaak_f32 v56, v252, v56, 0xc0135761
	v_mul_f32_e32 v54, v48, v54
	v_mul_f32_e32 v56, v45, v56
	v_exp_f32_e32 v55, v55
	v_exp_f32_e32 v54, v54
	v_exp_f32_e32 v58, v56
	v_add_f32_e32 v55, 1.0, v55
	v_rcp_f32_e32 v50, v50
	v_rcp_f32_e32 v51, v51
	v_rcp_f32_e32 v53, v53
	v_add_f32_e32 v54, 1.0, v54
	v_rcp_f32_e32 v56, v55
	v_add_f32_e32 v55, 1.0, v57
	v_add_f32_e32 v57, 1.0, v58
	v_rcp_f32_e32 v54, v54
	v_rcp_f32_e32 v55, v55
	v_rcp_f32_e32 v57, v57
	v_pk_mul_f32 v[46:47], v[46:47], v[50:51]
	v_pk_mul_f32 v[50:51], v[42:43], v[52:53]
	v_lshl_add_u64 v[42:43], v[106:107], 0, v[68:69]
	v_pk_mul_f32 v[48:49], v[48:49], v[54:55]
	v_pk_mul_f32 v[52:53], v[44:45], v[56:57]
	v_lshlrev_b64 v[42:43], 10, v[42:43]
; __device__ __forceinline__ void store8(bf16_t* p, const f32x4& a, const f32x4& b) { u32x4 w; w.x = pk2(a[0], a[1]); w.y = pk2(a[2], a[3]); w.z = pk2(b[0], b[1]); w.w = pk2(b[2], b[3]); *(u32x4*)p = w; }
; __device__ __forceinline__ float gelu_t(float x) { const float u = x + 0.044715f * x * x * x; return x * __builtin_amdgcn_rcpf(1.f + __builtin_amdgcn_exp2f(-2.302208198f * u)); }
;     __device__ __forceinline__ void operator()(const f32x4 (&acc)[2][2][4][2], const pg8::Unit& u, int wr, int wc, int fr, int fq, int buf) const {
;     ...
;                     for (int m = 0; m < 4; ++m) { const int cr = j9 * 256 + ai * 128 + m * 16 + rloc0, b = cr / 144, c = cr - b * 144;
;                         f32x4 v0 = acc[ai][bj][m][0], v1 = acc[ai][bj][m][1];
; #pragma unroll
;                         for (int q = 0; q < 4; ++q) { v0[q] = gelu_t(v0[q]); v1[q] = gelu_t(v1[q]); }
;                         store8(G + ((size_t)b * RB + 16 * c + t) * 512 + 16 * g + h0, v0, v1); } }
	v_lshl_add_u64 v[54:55], v[144:145], 0, v[42:43]
	v_cvt_pk_bf16_f32 v42, v46, v47
	v_cvt_pk_bf16_f32 v43, v48, v49
	v_cvt_pk_bf16_f32 v44, v50, v51
	v_cvt_pk_bf16_f32 v45, v52, v53
	v_mul_f32_e32 v46, v38, v38
	global_store_dwordx4 v[54:55], v[42:45], off
	v_fmaak_f32 v46, v252, v46, 0xc0135761
	v_mul_f32_e32 v46, v38, v46
	v_mul_f32_e32 v44, v39, v39
	v_fmaak_f32 v44, v252, v44, 0xc0135761
	v_mul_f32_e32 v44, v39, v44
	v_mul_f32_e32 v47, v34, v34
	v_exp_f32_e32 v46, v46
	v_fmaak_f32 v47, v252, v47, 0xc0135761
	v_exp_f32_e32 v45, v44
	v_mul_f32_e32 v44, v35, v35
	v_mul_f32_e32 v47, v34, v47
	v_fmaak_f32 v44, v252, v44, 0xc0135761
	v_mul_f32_e32 v44, v35, v44
	v_exp_f32_e32 v47, v47
	v_add_f32_e32 v42, 1.0, v46
	v_exp_f32_e32 v46, v44
	v_mul_f32_e32 v48, v41, v41
	v_fmaak_f32 v48, v252, v48, 0xc0135761
	v_mul_f32_e32 v48, v41, v48
	v_add_f32_e32 v43, 1.0, v47
	v_mul_f32_e32 v47, v36, v36
	v_rcp_f32_e32 v44, v43
	v_add_f32_e32 v43, 1.0, v45
	v_add_f32_e32 v45, 1.0, v46
	v_mul_f32_e32 v46, v40, v40
	v_fmaak_f32 v47, v252, v47, 0xc0135761
	v_exp_f32_e32 v49, v48
	v_mul_f32_e32 v48, v37, v37
	v_fmaak_f32 v46, v252, v46, 0xc0135761
	v_mul_f32_e32 v47, v36, v47
	v_fmaak_f32 v48, v252, v48, 0xc0135761
	v_mul_f32_e32 v46, v40, v46
	v_mul_f32_e32 v48, v37, v48
	v_exp_f32_e32 v47, v47
	v_exp_f32_e32 v46, v46
	v_exp_f32_e32 v50, v48
	v_add_f32_e32 v47, 1.0, v47
	v_rcp_f32_e32 v42, v42
	v_rcp_f32_e32 v43, v43
	v_rcp_f32_e32 v45, v45
	v_add_f32_e32 v46, 1.0, v46
	v_rcp_f32_e32 v48, v47
	v_add_f32_e32 v47, 1.0, v49
	v_add_f32_e32 v49, 1.0, v50
	v_rcp_f32_e32 v46, v46
	v_rcp_f32_e32 v47, v47
	v_rcp_f32_e32 v49, v49
	v_pk_mul_f32 v[38:39], v[38:39], v[42:43]
	v_pk_mul_f32 v[42:43], v[34:35], v[44:45]
	v_lshl_add_u64 v[34:35], v[98:99], 0, v[68:69]
	v_pk_mul_f32 v[40:41], v[40:41], v[46:47]
	v_pk_mul_f32 v[44:45], v[36:37], v[48:49]
	v_lshlrev_b64 v[34:35], 10, v[34:35]
	v_lshl_add_u64 v[46:47], v[144:145], 0, v[34:35]
	v_cvt_pk_bf16_f32 v34, v38, v39
	v_cvt_pk_bf16_f32 v35, v40, v41
	v_cvt_pk_bf16_f32 v36, v42, v43
	v_cvt_pk_bf16_f32 v37, v44, v45
	v_mul_f32_e32 v38, v30, v30
	global_store_dwordx4 v[46:47], v[34:37], off
	v_fmaak_f32 v38, v252, v38, 0xc0135761
	v_mul_f32_e32 v38, v30, v38
	v_mul_f32_e32 v36, v31, v31
	v_fmaak_f32 v36, v252, v36, 0xc0135761
	v_mul_f32_e32 v36, v31, v36
	v_mul_f32_e32 v39, v26, v26
	v_exp_f32_e32 v38, v38
	v_fmaak_f32 v39, v252, v39, 0xc0135761
	v_exp_f32_e32 v37, v36
	v_mul_f32_e32 v36, v27, v27
	v_mul_f32_e32 v39, v26, v39
	v_fmaak_f32 v36, v252, v36, 0xc0135761
	v_mul_f32_e32 v36, v27, v36
	v_exp_f32_e32 v39, v39
	v_add_f32_e32 v34, 1.0, v38
	v_exp_f32_e32 v38, v36
	v_mul_f32_e32 v40, v33, v33
	v_fmaak_f32 v40, v252, v40, 0xc0135761
	v_mul_f32_e32 v40, v33, v40
	v_add_f32_e32 v35, 1.0, v39
	v_mul_f32_e32 v39, v28, v28
	v_rcp_f32_e32 v36, v35
	v_add_f32_e32 v35, 1.0, v37
	v_add_f32_e32 v37, 1.0, v38
	v_mul_f32_e32 v38, v32, v32
	v_fmaak_f32 v39, v252, v39, 0xc0135761
	v_exp_f32_e32 v41, v40
	v_mul_f32_e32 v40, v29, v29
	v_fmaak_f32 v38, v252, v38, 0xc0135761
	v_mul_f32_e32 v39, v28, v39
	v_fmaak_f32 v40, v252, v40, 0xc0135761
	v_mul_f32_e32 v38, v32, v38
	v_mul_f32_e32 v40, v29, v40
	v_exp_f32_e32 v39, v39
	v_exp_f32_e32 v38, v38
	v_exp_f32_e32 v42, v40
	v_add_f32_e32 v39, 1.0, v39
	v_rcp_f32_e32 v34, v34
	v_rcp_f32_e32 v35, v35
	v_rcp_f32_e32 v37, v37
	v_add_f32_e32 v38, 1.0, v38
	v_rcp_f32_e32 v40, v39
	v_add_f32_e32 v39, 1.0, v41
	v_add_f32_e32 v41, 1.0, v42
	v_rcp_f32_e32 v38, v38
	v_rcp_f32_e32 v39, v39
	v_rcp_f32_e32 v41, v41
	v_pk_mul_f32 v[30:31], v[30:31], v[34:35]
	v_pk_mul_f32 v[34:35], v[26:27], v[36:37]
	v_lshl_add_u64 v[26:27], v[90:91], 0, v[68:69]
	v_pk_mul_f32 v[32:33], v[32:33], v[38:39]
	v_pk_mul_f32 v[36:37], v[28:29], v[40:41]
	v_lshlrev_b64 v[26:27], 10, v[26:27]
	v_lshl_add_u64 v[38:39], v[144:145], 0, v[26:27]
	v_cvt_pk_bf16_f32 v26, v30, v31
	v_cvt_pk_bf16_f32 v27, v32, v33
	v_cvt_pk_bf16_f32 v28, v34, v35
	v_cvt_pk_bf16_f32 v29, v36, v37
	v_mul_f32_e32 v30, v22, v22
	global_store_dwordx4 v[38:39], v[26:29], off
	v_fmaak_f32 v30, v252, v30, 0xc0135761
	v_mul_f32_e32 v30, v22, v30
	v_mul_f32_e32 v28, v23, v23
	v_fmaak_f32 v28, v252, v28, 0xc0135761
	v_mul_f32_e32 v28, v23, v28
	v_mul_f32_e32 v31, v18, v18
	v_exp_f32_e32 v30, v30
	v_fmaak_f32 v31, v252, v31, 0xc0135761
	v_exp_f32_e32 v29, v28
	v_mul_f32_e32 v28, v19, v19
	v_mul_f32_e32 v31, v18, v31
	v_fmaak_f32 v28, v252, v28, 0xc0135761
	v_mul_f32_e32 v28, v19, v28
	v_exp_f32_e32 v31, v31
	v_add_f32_e32 v26, 1.0, v30
	v_exp_f32_e32 v30, v28
	v_mul_f32_e32 v32, v25, v25
	v_fmaak_f32 v32, v252, v32, 0xc0135761
	v_mul_f32_e32 v32, v25, v32
	v_add_f32_e32 v27, 1.0, v31
	v_mul_f32_e32 v31, v20, v20
	v_rcp_f32_e32 v28, v27
	v_add_f32_e32 v27, 1.0, v29
	v_add_f32_e32 v29, 1.0, v30
	v_mul_f32_e32 v30, v24, v24
	v_fmaak_f32 v31, v252, v31, 0xc0135761
	v_exp_f32_e32 v33, v32
	v_mul_f32_e32 v32, v21, v21
; __device__ __forceinline__ void store8(bf16_t* p, const f32x4& a, const f32x4& b) { u32x4 w; w.x = pk2(a[0], a[1]); w.y = pk2(a[2], a[3]); w.z = pk2(b[0], b[1]); w.w = pk2(b[2], b[3]); *(u32x4*)p = w; }
; __device__ __forceinline__ float gelu_t(float x) { const float u = x + 0.044715f * x * x * x; return x * __builtin_amdgcn_rcpf(1.f + __builtin_amdgcn_exp2f(-2.302208198f * u)); }
;     __device__ __forceinline__ void operator()(const f32x4 (&acc)[2][2][4][2], const pg8::Unit& u, int wr, int wc, int fr, int fq, int buf) const {
;     ...
;                     for (int m = 0; m < 4; ++m) { const int cr = j9 * 256 + ai * 128 + m * 16 + rloc0, b = cr / 144, c = cr - b * 144;
;                         f32x4 v0 = acc[ai][bj][m][0], v1 = acc[ai][bj][m][1];
; #pragma unroll
;                         for (int q = 0; q < 4; ++q) { v0[q] = gelu_t(v0[q]); v1[q] = gelu_t(v1[q]); }
;                         store8(G + ((size_t)b * RB + 16 * c + t) * 512 + 16 * g + h0, v0, v1); } }
	v_fmaak_f32 v30, v252, v30, 0xc0135761
	v_mul_f32_e32 v31, v20, v31
	v_fmaak_f32 v32, v252, v32, 0xc0135761
	v_mul_f32_e32 v30, v24, v30
	v_mul_f32_e32 v32, v21, v32
	v_exp_f32_e32 v31, v31
	v_exp_f32_e32 v30, v30
	v_exp_f32_e32 v34, v32
	v_add_f32_e32 v31, 1.0, v31
	v_rcp_f32_e32 v26, v26
	v_rcp_f32_e32 v27, v27
	v_rcp_f32_e32 v29, v29
	v_add_f32_e32 v30, 1.0, v30
	v_rcp_f32_e32 v32, v31
	v_add_f32_e32 v31, 1.0, v33
	v_add_f32_e32 v33, 1.0, v34
	v_rcp_f32_e32 v30, v30
	v_rcp_f32_e32 v31, v31
	v_rcp_f32_e32 v33, v33
	v_pk_mul_f32 v[22:23], v[22:23], v[26:27]
	v_pk_mul_f32 v[26:27], v[18:19], v[28:29]
	v_lshl_add_u64 v[18:19], v[82:83], 0, v[68:69]
	v_pk_mul_f32 v[24:25], v[24:25], v[30:31]
	v_pk_mul_f32 v[28:29], v[20:21], v[32:33]
	v_lshlrev_b64 v[18:19], 10, v[18:19]
	v_lshl_add_u64 v[30:31], v[144:145], 0, v[18:19]
	v_cvt_pk_bf16_f32 v18, v22, v23
	v_cvt_pk_bf16_f32 v19, v24, v25
	v_cvt_pk_bf16_f32 v20, v26, v27
	v_cvt_pk_bf16_f32 v21, v28, v29
	v_mul_f32_e32 v22, v14, v14
	global_store_dwordx4 v[30:31], v[18:21], off
	v_fmaak_f32 v22, v252, v22, 0xc0135761
	v_mul_f32_e32 v22, v14, v22
	v_mul_f32_e32 v20, v15, v15
	v_fmaak_f32 v20, v252, v20, 0xc0135761
	v_mul_f32_e32 v20, v15, v20
	v_mul_f32_e32 v23, v10, v10
	v_exp_f32_e32 v22, v22
	v_fmaak_f32 v23, v252, v23, 0xc0135761
	v_exp_f32_e32 v21, v20
	v_mul_f32_e32 v20, v11, v11
	v_mul_f32_e32 v23, v10, v23
	v_fmaak_f32 v20, v252, v20, 0xc0135761
	v_mul_f32_e32 v20, v11, v20
	v_exp_f32_e32 v23, v23
	v_add_f32_e32 v18, 1.0, v22
	v_exp_f32_e32 v22, v20
	v_mul_f32_e32 v24, v17, v17
	v_fmaak_f32 v24, v252, v24, 0xc0135761
	v_mul_f32_e32 v24, v17, v24
	v_add_f32_e32 v19, 1.0, v23
	v_mul_f32_e32 v23, v12, v12
	v_rcp_f32_e32 v20, v19
	v_add_f32_e32 v19, 1.0, v21
	v_add_f32_e32 v21, 1.0, v22
	v_mul_f32_e32 v22, v16, v16
	v_fmaak_f32 v23, v252, v23, 0xc0135761
	v_exp_f32_e32 v25, v24
	v_mul_f32_e32 v24, v13, v13
	v_fmaak_f32 v22, v252, v22, 0xc0135761
	v_mul_f32_e32 v23, v12, v23
	v_fmaak_f32 v24, v252, v24, 0xc0135761
	v_mul_f32_e32 v22, v16, v22
	v_mul_f32_e32 v24, v13, v24
	v_exp_f32_e32 v23, v23
	v_exp_f32_e32 v22, v22
	v_exp_f32_e32 v26, v24
	v_add_f32_e32 v23, 1.0, v23
	v_rcp_f32_e32 v18, v18
	v_rcp_f32_e32 v19, v19
	v_rcp_f32_e32 v21, v21
	v_add_f32_e32 v22, 1.0, v22
	v_rcp_f32_e32 v24, v23
	v_add_f32_e32 v23, 1.0, v25
	v_add_f32_e32 v25, 1.0, v26
	v_rcp_f32_e32 v22, v22
	v_rcp_f32_e32 v23, v23
	v_rcp_f32_e32 v25, v25
	v_pk_mul_f32 v[14:15], v[14:15], v[18:19]
	v_pk_mul_f32 v[18:19], v[10:11], v[20:21]
	v_lshl_add_u64 v[10:11], v[74:75], 0, v[68:69]
	v_pk_mul_f32 v[16:17], v[16:17], v[22:23]
	v_pk_mul_f32 v[20:21], v[12:13], v[24:25]
	v_lshlrev_b64 v[10:11], 10, v[10:11]
	v_lshl_add_u64 v[22:23], v[144:145], 0, v[10:11]
	v_cvt_pk_bf16_f32 v10, v14, v15
	v_cvt_pk_bf16_f32 v11, v16, v17
	v_cvt_pk_bf16_f32 v12, v18, v19
	v_cvt_pk_bf16_f32 v13, v20, v21
	v_mul_f32_e32 v14, v6, v6
	global_store_dwordx4 v[22:23], v[10:13], off
	v_fmaak_f32 v14, v252, v14, 0xc0135761
	v_mul_f32_e32 v14, v6, v14
	v_mul_f32_e32 v12, v7, v7
	v_fmaak_f32 v12, v252, v12, 0xc0135761
	v_mul_f32_e32 v12, v7, v12
	v_mul_f32_e32 v15, v2, v2
	v_exp_f32_e32 v14, v14
	v_fmaak_f32 v15, v252, v15, 0xc0135761
	v_exp_f32_e32 v13, v12
	v_mul_f32_e32 v12, v3, v3
	v_mul_f32_e32 v15, v2, v15
	v_fmaak_f32 v12, v252, v12, 0xc0135761
	v_mul_f32_e32 v12, v3, v12
	v_exp_f32_e32 v15, v15
	v_add_f32_e32 v10, 1.0, v14
	v_exp_f32_e32 v14, v12
	v_mul_f32_e32 v16, v9, v9
	v_fmaak_f32 v16, v252, v16, 0xc0135761
	v_mul_f32_e32 v16, v9, v16
	v_add_f32_e32 v11, 1.0, v15
	v_mul_f32_e32 v15, v4, v4
	v_rcp_f32_e32 v12, v11
	v_add_f32_e32 v11, 1.0, v13
	v_add_f32_e32 v13, 1.0, v14
	v_mul_f32_e32 v14, v8, v8
	v_fmaak_f32 v15, v252, v15, 0xc0135761
	v_exp_f32_e32 v17, v16
	v_mul_f32_e32 v16, v5, v5
	v_fmaak_f32 v14, v252, v14, 0xc0135761
	v_mul_f32_e32 v15, v4, v15
	v_fmaak_f32 v16, v252, v16, 0xc0135761
	v_mul_f32_e32 v14, v8, v14
	v_mul_f32_e32 v16, v5, v16
	v_exp_f32_e32 v15, v15
	v_exp_f32_e32 v14, v14
	v_exp_f32_e32 v18, v16
	v_add_f32_e32 v15, 1.0, v15
	v_rcp_f32_e32 v10, v10
	v_rcp_f32_e32 v11, v11
	v_rcp_f32_e32 v13, v13
	v_add_f32_e32 v14, 1.0, v14
	v_rcp_f32_e32 v16, v15
	v_add_f32_e32 v15, 1.0, v17
	v_add_f32_e32 v17, 1.0, v18
	v_rcp_f32_e32 v14, v14
	v_rcp_f32_e32 v15, v15
	v_rcp_f32_e32 v17, v17
	v_pk_mul_f32 v[6:7], v[6:7], v[10:11]
	v_pk_mul_f32 v[10:11], v[2:3], v[12:13]
	v_lshl_add_u64 v[2:3], v[66:67], 0, v[68:69]
	v_pk_mul_f32 v[8:9], v[8:9], v[14:15]
	v_pk_mul_f32 v[12:13], v[4:5], v[16:17]
	v_lshlrev_b64 v[2:3], 10, v[2:3]
	v_lshl_add_u64 v[14:15], v[144:145], 0, v[2:3]
	v_cvt_pk_bf16_f32 v2, v6, v7
	v_cvt_pk_bf16_f32 v3, v8, v9
	v_cvt_pk_bf16_f32 v4, v10, v11
	v_cvt_pk_bf16_f32 v5, v12, v13
	s_andn2_b64 vcc, exec, s[58:59]
	s_mov_b64 s[58:59], -1
	global_store_dwordx4 v[14:15], v[2:5], off
	s_cbranch_vccnz .LBB0_859
	s_andn2_b64 vcc, exec, s[16:17]
	s_cbranch_vccnz .LBB0_858
	s_barrier
	s_branch .LBB0_858
